# static priority raise: one s_setprio 1 for waves 4-7 before the GEMM loop, per-segment flips removed
# baseline (speedup 1.0000x reference)
.LBB0_512:
	s_cmp_eq_u32 s10, 1
	s_cbranch_scc0 .Lsprio_skip
	s_setprio 1

.LBB0_522:
	s_add_i32 s72, s78, 2
	s_add_u32 s79, s10, 0x80
	s_addc_u32 vcc_lo, s11, 0
	v_add_u32_e32 v148, 0x10000, v185
	s_cmp_eq_u32 s15, s78
	s_cselect_b32 s78, s12, s84
	s_cselect_b32 vcc_hi, s49, vcc_lo
	s_cselect_b32 vcc_lo, s48, s79
	s_cselect_b32 s79, s13, s85
	ds_read_b128 v[128:131], v148 offset:0
	ds_read_b128 v[132:135], v148 offset:1024
	ds_read_b128 v[136:139], v148 offset:2048
	ds_read_b128 v[140:143], v148 offset:3072
	ds_read_b128 v[218:221], v148 offset:16384
	ds_read_b128 v[222:225], v148 offset:17408
	ds_read_b128 v[226:229], v148 offset:18432
	ds_read_b128 v[230:233], v148 offset:19456
	ds_read_b128 v[162:165], v188 offset:0
	ds_read_b128 v[190:193], v188 offset:1024
	ds_read_b128 v[194:197], v188 offset:2048
	ds_read_b128 v[198:201], v188 offset:3072
	ds_read_b128 v[202:205], v188 offset:4096
	ds_read_b128 v[206:209], v188 offset:5120
	ds_read_b128 v[210:213], v188 offset:6144
	ds_read_b128 v[214:217], v188 offset:7168
	s_add_u32 s4, s10, s26
	s_addc_u32 s5, s11, 0
	s_add_i32 m0, s81, 0xc000
	s_nop 0
	global_load_lds_dwordx4 v152, s[4:5]
	s_add_i32 m0, s81, 0xe000
	s_nop 0
	global_load_lds_dwordx4 v144, s[4:5]
	s_waitcnt vmcnt(8)
	s_waitcnt lgkmcnt(0)
	s_barrier
	v_mfma_f32_16x16x32_bf16 v[124:127], v[128:131], v[162:165], v[124:127]
	v_mfma_f32_16x16x32_bf16 v[116:119], v[136:139], v[162:165], v[116:119]
	v_mfma_f32_16x16x32_bf16 v[120:123], v[128:131], v[194:197], v[120:123]
	v_mfma_f32_16x16x32_bf16 v[112:115], v[136:139], v[194:197], v[112:115]
	v_mfma_f32_16x16x32_bf16 v[92:95], v[128:131], v[202:205], v[92:95]
	v_mfma_f32_16x16x32_bf16 v[84:87], v[136:139], v[202:205], v[84:87]
	v_mfma_f32_16x16x32_bf16 v[88:91], v[128:131], v[210:213], v[88:91]
	v_mfma_f32_16x16x32_bf16 v[80:83], v[136:139], v[210:213], v[80:83]
	v_mfma_f32_16x16x32_bf16 v[124:127], v[132:135], v[190:193], v[124:127]
	v_mfma_f32_16x16x32_bf16 v[116:119], v[140:143], v[190:193], v[116:119]
	v_mfma_f32_16x16x32_bf16 v[120:123], v[132:135], v[198:201], v[120:123]
	v_mfma_f32_16x16x32_bf16 v[112:115], v[140:143], v[198:201], v[112:115]
	v_mfma_f32_16x16x32_bf16 v[92:95], v[132:135], v[206:209], v[92:95]
	v_mfma_f32_16x16x32_bf16 v[84:87], v[140:143], v[206:209], v[84:87]
	v_mfma_f32_16x16x32_bf16 v[88:91], v[132:135], v[214:217], v[88:91]
	v_mfma_f32_16x16x32_bf16 v[80:83], v[140:143], v[214:217], v[80:83]
	v_mfma_f32_16x16x32_bf16 v[108:111], v[218:221], v[162:165], v[108:111]
	v_mfma_f32_16x16x32_bf16 v[100:103], v[226:229], v[162:165], v[100:103]
	v_mfma_f32_16x16x32_bf16 v[104:107], v[218:221], v[194:197], v[104:107]
	v_mfma_f32_16x16x32_bf16 v[96:99], v[226:229], v[194:197], v[96:99]
	v_mfma_f32_16x16x32_bf16 v[76:79], v[218:221], v[202:205], v[76:79]
	v_mfma_f32_16x16x32_bf16 v[68:71], v[226:229], v[202:205], v[68:71]
	v_mfma_f32_16x16x32_bf16 v[72:75], v[218:221], v[210:213], v[72:75]
	v_mfma_f32_16x16x32_bf16 v[64:67], v[226:229], v[210:213], v[64:67]
	v_mfma_f32_16x16x32_bf16 v[108:111], v[222:225], v[190:193], v[108:111]
	v_mfma_f32_16x16x32_bf16 v[100:103], v[230:233], v[190:193], v[100:103]
	v_mfma_f32_16x16x32_bf16 v[104:107], v[222:225], v[198:201], v[104:107]
	v_mfma_f32_16x16x32_bf16 v[96:99], v[230:233], v[198:201], v[96:99]
	v_mfma_f32_16x16x32_bf16 v[76:79], v[222:225], v[206:209], v[76:79]
	v_mfma_f32_16x16x32_bf16 v[68:71], v[230:233], v[206:209], v[68:71]
	v_mfma_f32_16x16x32_bf16 v[72:75], v[222:225], v[214:217], v[72:75]
	v_mfma_f32_16x16x32_bf16 v[64:67], v[230:233], v[214:217], v[64:67]
	s_barrier
	ds_read_b128 v[162:165], v188 offset:16384
	ds_read_b128 v[190:193], v188 offset:17408
	ds_read_b128 v[194:197], v188 offset:18432
	ds_read_b128 v[198:201], v188 offset:19456
	ds_read_b128 v[202:205], v188 offset:20480
	ds_read_b128 v[206:209], v188 offset:21504
	ds_read_b128 v[210:213], v188 offset:22528
	ds_read_b128 v[214:217], v188 offset:23552
	s_add_i32 m0, s81, 0x10000
	s_nop 0
	global_load_lds_dwordx4 v154, s[78:79]
	s_add_i32 m0, s81, 0x12000
	s_nop 0
	global_load_lds_dwordx4 v146, s[78:79]
	s_add_i32 m0, s81, 0x0
	s_nop 0
	global_load_lds_dwordx4 v152, vcc
	s_add_i32 m0, s81, 0x2000
	s_nop 0
	global_load_lds_dwordx4 v144, vcc
	s_add_u32 s4, s78, s26
	s_addc_u32 s5, s79, 0
	s_add_i32 m0, s81, 0x14000
	s_nop 0
	global_load_lds_dwordx4 v154, s[4:5]
	s_add_i32 m0, s81, 0x16000
	s_nop 0
	global_load_lds_dwordx4 v146, s[4:5]
	s_waitcnt vmcnt(8)
	s_waitcnt lgkmcnt(0)
	s_barrier
	v_mfma_f32_16x16x32_bf16 v[60:63], v[128:131], v[162:165], v[60:63]
	v_mfma_f32_16x16x32_bf16 v[56:59], v[136:139], v[162:165], v[56:59]
	v_mfma_f32_16x16x32_bf16 v[52:55], v[128:131], v[194:197], v[52:55]
	v_mfma_f32_16x16x32_bf16 v[48:51], v[136:139], v[194:197], v[48:51]
	v_mfma_f32_16x16x32_bf16 v[28:31], v[128:131], v[202:205], v[28:31]
	v_mfma_f32_16x16x32_bf16 v[20:23], v[136:139], v[202:205], v[20:23]
	v_mfma_f32_16x16x32_bf16 v[24:27], v[128:131], v[210:213], v[24:27]
	v_mfma_f32_16x16x32_bf16 v[16:19], v[136:139], v[210:213], v[16:19]
	v_mfma_f32_16x16x32_bf16 v[60:63], v[132:135], v[190:193], v[60:63]
	v_mfma_f32_16x16x32_bf16 v[56:59], v[140:143], v[190:193], v[56:59]
	v_mfma_f32_16x16x32_bf16 v[52:55], v[132:135], v[198:201], v[52:55]
	v_mfma_f32_16x16x32_bf16 v[48:51], v[140:143], v[198:201], v[48:51]
	v_mfma_f32_16x16x32_bf16 v[28:31], v[132:135], v[206:209], v[28:31]
	v_mfma_f32_16x16x32_bf16 v[20:23], v[140:143], v[206:209], v[20:23]
	v_mfma_f32_16x16x32_bf16 v[24:27], v[132:135], v[214:217], v[24:27]
	v_mfma_f32_16x16x32_bf16 v[16:19], v[140:143], v[214:217], v[16:19]
	v_mfma_f32_16x16x32_bf16 v[44:47], v[218:221], v[162:165], v[44:47]
	v_mfma_f32_16x16x32_bf16 v[36:39], v[226:229], v[162:165], v[36:39]
	v_mfma_f32_16x16x32_bf16 v[40:43], v[218:221], v[194:197], v[40:43]
	v_mfma_f32_16x16x32_bf16 v[32:35], v[226:229], v[194:197], v[32:35]
	v_mfma_f32_16x16x32_bf16 v[12:15], v[218:221], v[202:205], v[12:15]
	v_mfma_f32_16x16x32_bf16 v[4:7], v[226:229], v[202:205], v[4:7]
	v_mfma_f32_16x16x32_bf16 v[8:11], v[218:221], v[210:213], v[8:11]
	v_mfma_f32_16x16x32_bf16 v[0:3], v[226:229], v[210:213], v[0:3]
	v_mfma_f32_16x16x32_bf16 v[44:47], v[222:225], v[190:193], v[44:47]
	v_mfma_f32_16x16x32_bf16 v[36:39], v[230:233], v[190:193], v[36:39]
	v_mfma_f32_16x16x32_bf16 v[40:43], v[222:225], v[198:201], v[40:43]
	v_mfma_f32_16x16x32_bf16 v[32:35], v[230:233], v[198:201], v[32:35]
	v_mfma_f32_16x16x32_bf16 v[12:15], v[222:225], v[206:209], v[12:15]
	v_mfma_f32_16x16x32_bf16 v[4:7], v[230:233], v[206:209], v[4:7]
	v_mfma_f32_16x16x32_bf16 v[8:11], v[222:225], v[214:217], v[8:11]
	v_mfma_f32_16x16x32_bf16 v[0:3], v[230:233], v[214:217], v[0:3]
	s_barrier
	ds_read_b128 v[128:131], v148 offset:32768
	ds_read_b128 v[132:135], v148 offset:33792
	ds_read_b128 v[136:139], v148 offset:34816
	ds_read_b128 v[140:143], v148 offset:35840
	ds_read_b128 v[218:221], v148 offset:49152
	ds_read_b128 v[222:225], v148 offset:50176
	ds_read_b128 v[226:229], v148 offset:51200
	ds_read_b128 v[230:233], v148 offset:52224
	ds_read_b128 v[162:165], v188 offset:32768
	ds_read_b128 v[190:193], v188 offset:33792
	ds_read_b128 v[194:197], v188 offset:34816
	ds_read_b128 v[198:201], v188 offset:35840
	ds_read_b128 v[202:205], v188 offset:36864
	ds_read_b128 v[206:209], v188 offset:37888
	ds_read_b128 v[210:213], v188 offset:38912
	ds_read_b128 v[214:217], v188 offset:39936
	s_add_u32 s4, vcc_lo, s26
	s_addc_u32 s5, vcc_hi, 0
	s_add_i32 m0, s81, 0x4000
	s_nop 0
	global_load_lds_dwordx4 v152, s[4:5]
	s_add_i32 m0, s81, 0x6000
	s_nop 0
	global_load_lds_dwordx4 v144, s[4:5]
	s_waitcnt vmcnt(8)
	s_waitcnt lgkmcnt(0)
	s_barrier
	v_mfma_f32_16x16x32_bf16 v[124:127], v[128:131], v[162:165], v[124:127]
	v_mfma_f32_16x16x32_bf16 v[116:119], v[136:139], v[162:165], v[116:119]
	v_mfma_f32_16x16x32_bf16 v[120:123], v[128:131], v[194:197], v[120:123]
	v_mfma_f32_16x16x32_bf16 v[112:115], v[136:139], v[194:197], v[112:115]
	v_mfma_f32_16x16x32_bf16 v[92:95], v[128:131], v[202:205], v[92:95]
	v_mfma_f32_16x16x32_bf16 v[84:87], v[136:139], v[202:205], v[84:87]
	v_mfma_f32_16x16x32_bf16 v[88:91], v[128:131], v[210:213], v[88:91]
	v_mfma_f32_16x16x32_bf16 v[80:83], v[136:139], v[210:213], v[80:83]
	v_mfma_f32_16x16x32_bf16 v[124:127], v[132:135], v[190:193], v[124:127]
	v_mfma_f32_16x16x32_bf16 v[116:119], v[140:143], v[190:193], v[116:119]
	v_mfma_f32_16x16x32_bf16 v[120:123], v[132:135], v[198:201], v[120:123]
	v_mfma_f32_16x16x32_bf16 v[112:115], v[140:143], v[198:201], v[112:115]
	v_mfma_f32_16x16x32_bf16 v[92:95], v[132:135], v[206:209], v[92:95]
	v_mfma_f32_16x16x32_bf16 v[84:87], v[140:143], v[206:209], v[84:87]
	v_mfma_f32_16x16x32_bf16 v[88:91], v[132:135], v[214:217], v[88:91]
	v_mfma_f32_16x16x32_bf16 v[80:83], v[140:143], v[214:217], v[80:83]
	v_mfma_f32_16x16x32_bf16 v[108:111], v[218:221], v[162:165], v[108:111]
	v_mfma_f32_16x16x32_bf16 v[100:103], v[226:229], v[162:165], v[100:103]
	v_mfma_f32_16x16x32_bf16 v[104:107], v[218:221], v[194:197], v[104:107]
	v_mfma_f32_16x16x32_bf16 v[96:99], v[226:229], v[194:197], v[96:99]
	v_mfma_f32_16x16x32_bf16 v[76:79], v[218:221], v[202:205], v[76:79]
	v_mfma_f32_16x16x32_bf16 v[68:71], v[226:229], v[202:205], v[68:71]
	v_mfma_f32_16x16x32_bf16 v[72:75], v[218:221], v[210:213], v[72:75]
	v_mfma_f32_16x16x32_bf16 v[64:67], v[226:229], v[210:213], v[64:67]
	v_mfma_f32_16x16x32_bf16 v[108:111], v[222:225], v[190:193], v[108:111]
	v_mfma_f32_16x16x32_bf16 v[100:103], v[230:233], v[190:193], v[100:103]
	v_mfma_f32_16x16x32_bf16 v[104:107], v[222:225], v[198:201], v[104:107]
	v_mfma_f32_16x16x32_bf16 v[96:99], v[230:233], v[198:201], v[96:99]
	v_mfma_f32_16x16x32_bf16 v[76:79], v[222:225], v[206:209], v[76:79]
	v_mfma_f32_16x16x32_bf16 v[68:71], v[230:233], v[206:209], v[68:71]
	v_mfma_f32_16x16x32_bf16 v[72:75], v[222:225], v[214:217], v[72:75]
	v_mfma_f32_16x16x32_bf16 v[64:67], v[230:233], v[214:217], v[64:67]
	s_barrier
	ds_read_b128 v[162:165], v188 offset:49152
	ds_read_b128 v[190:193], v188 offset:50176
	ds_read_b128 v[194:197], v188 offset:51200
	ds_read_b128 v[198:201], v188 offset:52224
	ds_read_b128 v[202:205], v188 offset:53248
	ds_read_b128 v[206:209], v188 offset:54272
	ds_read_b128 v[210:213], v188 offset:55296
	ds_read_b128 v[214:217], v188 offset:56320
	s_add_u32 s4, s78, 0x80
	s_addc_u32 s5, s79, 0
	s_add_i32 m0, s81, 0x18000
	s_nop 0
	global_load_lds_dwordx4 v154, s[4:5]
	s_add_i32 m0, s81, 0x1a000
	s_nop 0
	global_load_lds_dwordx4 v146, s[4:5]
	s_add_u32 s4, vcc_lo, 0x80
	s_addc_u32 s5, vcc_hi, 0
	s_add_i32 m0, s81, 0x8000
	s_nop 0
	global_load_lds_dwordx4 v152, s[4:5]
	s_add_i32 m0, s81, 0xa000
	s_nop 0
	global_load_lds_dwordx4 v144, s[4:5]
	s_add_u32 s4, s78, s26
	s_addc_u32 s5, s79, 0
	s_add_u32 s4, s4, 0x80
	s_addc_u32 s5, s5, 0
	s_add_i32 m0, s81, 0x1c000
	s_nop 0
	global_load_lds_dwordx4 v154, s[4:5]
	s_add_i32 m0, s81, 0x1e000
	s_nop 0
	global_load_lds_dwordx4 v146, s[4:5]
	s_waitcnt vmcnt(8)
	s_waitcnt lgkmcnt(0)
	s_barrier
	v_mfma_f32_16x16x32_bf16 v[60:63], v[128:131], v[162:165], v[60:63]
	v_mfma_f32_16x16x32_bf16 v[56:59], v[136:139], v[162:165], v[56:59]
	v_mfma_f32_16x16x32_bf16 v[52:55], v[128:131], v[194:197], v[52:55]
	v_mfma_f32_16x16x32_bf16 v[48:51], v[136:139], v[194:197], v[48:51]
	v_mfma_f32_16x16x32_bf16 v[28:31], v[128:131], v[202:205], v[28:31]
	v_mfma_f32_16x16x32_bf16 v[20:23], v[136:139], v[202:205], v[20:23]
	v_mfma_f32_16x16x32_bf16 v[24:27], v[128:131], v[210:213], v[24:27]
	v_mfma_f32_16x16x32_bf16 v[16:19], v[136:139], v[210:213], v[16:19]
	v_mfma_f32_16x16x32_bf16 v[60:63], v[132:135], v[190:193], v[60:63]
	v_mfma_f32_16x16x32_bf16 v[56:59], v[140:143], v[190:193], v[56:59]
	v_mfma_f32_16x16x32_bf16 v[52:55], v[132:135], v[198:201], v[52:55]
	v_mfma_f32_16x16x32_bf16 v[48:51], v[140:143], v[198:201], v[48:51]
	v_mfma_f32_16x16x32_bf16 v[28:31], v[132:135], v[206:209], v[28:31]
	v_mfma_f32_16x16x32_bf16 v[20:23], v[140:143], v[206:209], v[20:23]
	v_mfma_f32_16x16x32_bf16 v[24:27], v[132:135], v[214:217], v[24:27]
	v_mfma_f32_16x16x32_bf16 v[16:19], v[140:143], v[214:217], v[16:19]
	v_mfma_f32_16x16x32_bf16 v[44:47], v[218:221], v[162:165], v[44:47]
	v_mfma_f32_16x16x32_bf16 v[36:39], v[226:229], v[162:165], v[36:39]
	v_mfma_f32_16x16x32_bf16 v[40:43], v[218:221], v[194:197], v[40:43]
	v_mfma_f32_16x16x32_bf16 v[32:35], v[226:229], v[194:197], v[32:35]
	v_mfma_f32_16x16x32_bf16 v[12:15], v[218:221], v[202:205], v[12:15]
	v_mfma_f32_16x16x32_bf16 v[4:7], v[226:229], v[202:205], v[4:7]
	v_mfma_f32_16x16x32_bf16 v[8:11], v[218:221], v[210:213], v[8:11]
	v_mfma_f32_16x16x32_bf16 v[0:3], v[226:229], v[210:213], v[0:3]
	v_mfma_f32_16x16x32_bf16 v[44:47], v[222:225], v[190:193], v[44:47]
	v_mfma_f32_16x16x32_bf16 v[36:39], v[230:233], v[190:193], v[36:39]
	v_mfma_f32_16x16x32_bf16 v[40:43], v[222:225], v[198:201], v[40:43]
	v_mfma_f32_16x16x32_bf16 v[32:35], v[230:233], v[198:201], v[32:35]
	v_mfma_f32_16x16x32_bf16 v[12:15], v[222:225], v[206:209], v[12:15]
	v_mfma_f32_16x16x32_bf16 v[4:7], v[230:233], v[206:209], v[4:7]
	v_mfma_f32_16x16x32_bf16 v[8:11], v[222:225], v[214:217], v[8:11]
	v_mfma_f32_16x16x32_bf16 v[0:3], v[230:233], v[214:217], v[0:3]
	s_add_u32 s10, s10, 0x100
	s_addc_u32 s11, s11, 0
	s_add_u32 s84, s84, 0x100
	s_addc_u32 s85, s85, 0
	s_cmp_ge_u32 s72, s76
	s_mov_b32 s78, s72
	s_barrier
	s_cbranch_scc0 .LBB0_522
	v_lshl_add_u32 v162, s20, 8, v151
	s_cmp_lt_i32 s45, 2
	s_mov_b64 s[10:11], -1
	s_cbranch_scc1 .LBB0_537
	s_cmp_gt_i32 s45, 2
	s_cbranch_scc0 .LBB0_534
	s_add_i32 s10, s25, 2
	s_cmp_gt_u32 s10, 4
	s_mov_b64 s[10:11], -1
	s_cbranch_scc0 .LBB0_531
	s_add_i32 s10, s25, -3
	s_cmp_gt_u32 s10, 2
	v_lshl_or_b32 v148, s25, 8, v186
	s_mov_b64 s[10:11], -1
	s_cbranch_scc0 .LBB0_528
	v_ashrrev_i32_e32 v128, 31, v162
	v_mul_lo_u32 v134, s29, v162
	v_mul_lo_u32 v136, s28, v128
	v_mad_u64_u32 v[128:129], s[10:11], s28, v162, 0
	v_add3_u32 v129, v129, v136, v134
	v_lshl_add_u64 v[134:135], v[128:129], 1, s[70:71]
	v_ashrrev_i32_e32 v129, 31, v148
	v_mov_b32_e32 v128, v148
	v_lshlrev_b64 v[128:129], 1, v[128:129]
	v_cvt_pk_bf16_f32 v130, v124, v125
	v_cvt_pk_bf16_f32 v131, v126, v127
	v_cvt_pk_bf16_f32 v132, v116, v117
	v_cvt_pk_bf16_f32 v133, v118, v119
	v_lshl_add_u64 v[134:135], v[134:135], 0, v[128:129]
	global_store_dwordx4 v[134:135], v[130:133], off
	s_nop 1
	v_cvt_pk_bf16_f32 v130, v108, v109
	v_cvt_pk_bf16_f32 v131, v110, v111
	v_cvt_pk_bf16_f32 v132, v100, v101
	v_cvt_pk_bf16_f32 v133, v102, v103
	global_store_dwordx4 v[134:135], v[130:133], off offset:256
	v_or_b32_e32 v134, 16, v162
	v_mul_lo_u32 v137, s29, v134
	v_mad_u64_u32 v[134:135], s[10:11], s28, v134, 0
	v_add3_u32 v135, v135, v136, v137
	v_lshl_add_u64 v[134:135], v[134:135], 1, s[70:71]
	v_cvt_pk_bf16_f32 v130, v120, v121
	v_cvt_pk_bf16_f32 v131, v122, v123
	v_cvt_pk_bf16_f32 v132, v112, v113
	v_cvt_pk_bf16_f32 v133, v114, v115
	v_lshl_add_u64 v[134:135], v[134:135], 0, v[128:129]
	global_store_dwordx4 v[134:135], v[130:133], off
	s_nop 1
	v_cvt_pk_bf16_f32 v130, v104, v105
	v_cvt_pk_bf16_f32 v131, v106, v107
	v_cvt_pk_bf16_f32 v132, v96, v97
	v_cvt_pk_bf16_f32 v133, v98, v99
	global_store_dwordx4 v[134:135], v[130:133], off offset:256
	v_or_b32_e32 v134, 32, v162
	v_mul_lo_u32 v137, s29, v134
	v_mad_u64_u32 v[134:135], s[10:11], s28, v134, 0
	v_add3_u32 v135, v135, v136, v137
	v_lshl_add_u64 v[134:135], v[134:135], 1, s[70:71]
	v_cvt_pk_bf16_f32 v130, v92, v93
	v_cvt_pk_bf16_f32 v131, v94, v95
	v_cvt_pk_bf16_f32 v132, v84, v85
	v_cvt_pk_bf16_f32 v133, v86, v87
	v_lshl_add_u64 v[134:135], v[134:135], 0, v[128:129]
	global_store_dwordx4 v[134:135], v[130:133], off
	s_nop 1
	v_cvt_pk_bf16_f32 v130, v76, v77
	v_cvt_pk_bf16_f32 v131, v78, v79
	v_cvt_pk_bf16_f32 v132, v68, v69
	v_cvt_pk_bf16_f32 v133, v70, v71
	global_store_dwordx4 v[134:135], v[130:133], off offset:256
	v_or_b32_e32 v134, 48, v162
	v_mul_lo_u32 v137, s29, v134
	v_mad_u64_u32 v[134:135], s[10:11], s28, v134, 0
	v_add3_u32 v135, v135, v136, v137
	v_lshl_add_u64 v[134:135], v[134:135], 1, s[70:71]
	v_cvt_pk_bf16_f32 v130, v88, v89
	v_cvt_pk_bf16_f32 v131, v90, v91
	v_cvt_pk_bf16_f32 v132, v80, v81
	v_cvt_pk_bf16_f32 v133, v82, v83
	v_lshl_add_u64 v[134:135], v[134:135], 0, v[128:129]
	global_store_dwordx4 v[134:135], v[130:133], off
	s_nop 1
	v_cvt_pk_bf16_f32 v130, v72, v73
	v_cvt_pk_bf16_f32 v131, v74, v75
	v_cvt_pk_bf16_f32 v132, v64, v65
	v_cvt_pk_bf16_f32 v133, v66, v67
	global_store_dwordx4 v[134:135], v[130:133], off offset:256
	v_add_u32_e32 v134, 0x80, v162
	v_ashrrev_i32_e32 v135, 31, v134
	v_mul_lo_u32 v136, s28, v135
	v_mul_lo_u32 v137, s29, v134
	v_mad_u64_u32 v[134:135], s[10:11], s28, v134, 0
	v_add3_u32 v135, v135, v136, v137
	v_lshl_add_u64 v[134:135], v[134:135], 1, s[70:71]
	v_cvt_pk_bf16_f32 v130, v60, v61
	v_cvt_pk_bf16_f32 v131, v62, v63
	v_cvt_pk_bf16_f32 v132, v56, v57
	v_cvt_pk_bf16_f32 v133, v58, v59
	v_lshl_add_u64 v[134:135], v[134:135], 0, v[128:129]
	global_store_dwordx4 v[134:135], v[130:133], off
	s_nop 1
	v_cvt_pk_bf16_f32 v130, v44, v45
	v_cvt_pk_bf16_f32 v131, v46, v47
	v_cvt_pk_bf16_f32 v132, v36, v37
	v_cvt_pk_bf16_f32 v133, v38, v39
	global_store_dwordx4 v[134:135], v[130:133], off offset:256
	v_add_u32_e32 v134, 0x90, v162
	v_ashrrev_i32_e32 v135, 31, v134
	v_mul_lo_u32 v136, s28, v135
	v_mul_lo_u32 v137, s29, v134
	v_mad_u64_u32 v[134:135], s[10:11], s28, v134, 0
	v_add3_u32 v135, v135, v136, v137
	v_lshl_add_u64 v[134:135], v[134:135], 1, s[70:71]
	v_cvt_pk_bf16_f32 v130, v52, v53
	v_cvt_pk_bf16_f32 v131, v54, v55
	v_cvt_pk_bf16_f32 v132, v48, v49
	v_cvt_pk_bf16_f32 v133, v50, v51
	v_lshl_add_u64 v[134:135], v[134:135], 0, v[128:129]
	global_store_dwordx4 v[134:135], v[130:133], off
	s_nop 1
	v_cvt_pk_bf16_f32 v130, v40, v41
	v_cvt_pk_bf16_f32 v131, v42, v43
	v_cvt_pk_bf16_f32 v132, v32, v33
	v_cvt_pk_bf16_f32 v133, v34, v35
	global_store_dwordx4 v[134:135], v[130:133], off offset:256
	v_add_u32_e32 v134, 0xa0, v162
	v_ashrrev_i32_e32 v135, 31, v134
	v_mul_lo_u32 v136, s28, v135
	v_mul_lo_u32 v137, s29, v134
	v_mad_u64_u32 v[134:135], s[10:11], s28, v134, 0
	v_add3_u32 v135, v135, v136, v137
	v_lshl_add_u64 v[134:135], v[134:135], 1, s[70:71]
	v_cvt_pk_bf16_f32 v130, v28, v29
	v_cvt_pk_bf16_f32 v131, v30, v31
	v_cvt_pk_bf16_f32 v132, v20, v21
	v_cvt_pk_bf16_f32 v133, v22, v23
	v_lshl_add_u64 v[134:135], v[134:135], 0, v[128:129]
	global_store_dwordx4 v[134:135], v[130:133], off
	s_nop 1
	v_cvt_pk_bf16_f32 v130, v12, v13
	v_cvt_pk_bf16_f32 v131, v14, v15
	v_cvt_pk_bf16_f32 v132, v4, v5
	v_cvt_pk_bf16_f32 v133, v6, v7
	global_store_dwordx4 v[134:135], v[130:133], off offset:256
	v_add_u32_e32 v134, 0xb0, v162
	v_ashrrev_i32_e32 v135, 31, v134
	v_mul_lo_u32 v136, s28, v135
	v_mul_lo_u32 v137, s29, v134
	v_mad_u64_u32 v[134:135], s[10:11], s28, v134, 0
	v_add3_u32 v135, v135, v136, v137
	v_lshl_add_u64 v[134:135], v[134:135], 1, s[70:71]
	v_cvt_pk_bf16_f32 v130, v24, v25
	v_cvt_pk_bf16_f32 v131, v26, v27
	v_lshl_add_u64 v[134:135], v[134:135], 0, v[128:129]
	v_cvt_pk_bf16_f32 v132, v16, v17
	v_cvt_pk_bf16_f32 v133, v18, v19
	global_store_dwordx4 v[134:135], v[130:133], off
	v_cvt_pk_bf16_f32 v128, v8, v9
	v_cvt_pk_bf16_f32 v129, v10, v11
	s_mov_b64 s[10:11], 0
	s_nop 0
	v_cvt_pk_bf16_f32 v130, v0, v1
	v_cvt_pk_bf16_f32 v131, v2, v3
	global_store_dwordx4 v[134:135], v[128:131], off offset:256

.LBB0_549:
	s_setprio 0
	v_mov_b32_e32 v242, 0x8000
	v_mov_b32_e32 v243, 0x358637bd
	v_mov_b32_e32 v244, 0xfffe8000
	v_mov_b32_e32 v245, 0xffff4000
	v_mov_b32_e32 v246, 0xfffff500
	v_mov_b32_e32 v247, 0x41b17218
	v_mov_b32_e32 v168, 0x3a27c5ac
	v_mov_b32_e32 v170, 0x260
	v_mov_b32_e32 v176, 12
	v_mov_b32_e32 v178, 0xffffea00
	s_waitcnt vmcnt(0)
	v_readlane_b32 s76, v255, 10
	s_cmpk_gt_u32 s87, 0xff
	s_mov_b64 s[72:73], s[0:1]
	v_readlane_b32 s77, v255, 11
	s_mov_b32 s64, 0x2aaaaaab
	s_movk_i32 s94, 0x300
	s_movk_i32 s97, 0xea00
	s_movk_i32 s68, 0x200
	s_movk_i32 s83, 0x81
	s_cbranch_scc1 .LBB0_486
	s_barrier
	s_branch .LBB0_486
